# mLSTM V-staging thread assignment transposed (conflict-free LDS transpose writes); everything else as previous version
# speedup vs baseline: 1.1388x; 1.0071x over previous
; __device__ __forceinline__ int tid_() { int x = threadIdx.x; asm volatile("" : "+v"(x)); return x; }
; __device__ void mx_mlstm(const Params& P, int l, int item, char* lds) {
;     const int tid = tid_(), wid = tid >> 6, lane = tid & 63, fr = lane & 15, fq = lane >> 4;
;     const int b = item >> 3, h = (item >> 1) & 3, dsel = item & 1;
;     const bf16_t* pr = (const bf16_t*)(P.ws + OFF_PREST) + (size_t)b * SQ * PREST_LD;
;     bf16_t* YB = (bf16_t*)(P.ws + (dsel ? OFF_YB : OFF_Y1)) + (size_t)b * SQ * 512 + h * 128;
;     bf16_t* Q = (bf16_t*)lds; bf16_t* KP = Q + 64 * 72; bf16_t* KWT = KP + 64 * 72; bf16_t* VT = KWT + 64 * 72; bf16_t* CT = VT + 128 * 72;
;     float* NS = (float*)(CT + 128 * 72); float* E = NS + 64; float* MM = E + 64; float* SI = MM + 64; float* WI = SI + 64; float* FL = WI + 64; float* DEC = FL + 64;
;     const int i = wid * 16 + fr;
; #pragma unroll 1
;     for (int d = dsel; d <= dsel; ++d) {
;         f32x4 Cacc[8];
; #pragma unroll
;         for (int dt = 0; dt < 8; ++dt) Cacc[dt] = (f32x4){0.f, 0.f, 0.f, 0.f};
;         __syncthreads();
;         for (int e = tid; e < 128 * 72 / 2; e += NT) ((unsigned*)CT)[e] = 0u;
;         if (tid < 64) NS[tid] = 0.f;
;         float m_st = 0.f;
;         const float ib = P.in[I_MLIB][(l * 2 + d) * 4 + h], fb = P.in[I_MLFB][(l * 2 + d) * 4 + h];
;         __syncthreads();
; #pragma unroll 1
;     ...
;             for (int it = 0; it < 4; ++it) {
;                 const int vi = tid + 256 * it, ii = vi >> 4, e = vi & 15, t = TROW(ii);
;                 const u32x4 vv = *(const u32x4*)(pr + (size_t)t * PREST_LD + 512 + h * 128 + e * 8);
.LBB0_468:
	s_or_b64 exec, exec, s[0:1]
	v_lshlrev_b32_e32 v0, 3, v66
	s_waitcnt vmcnt(13)
	v_and_b32_e32 v2, 0x78, v0
	v_mul_u32_u24_e32 v3, 0x90, v2
	v_cmp_gt_i32_e32 vcc, 64, v66
	v_lshl_add_u32 v67, v66, 2, 0
	s_and_saveexec_b64 s[0:1], vcc
	ds_write_b32 v67, v1 offset:64512
	s_or_b64 exec, exec, s[0:1]
	s_lshl_b32 s0, s30, 8
	s_and_b32 s27, s0, 0x7800
	s_bfe_u32 s26, s30, 0x20001
	s_mul_i32 s0, s27, 0x2900
	v_readlane_b32 s28, v241, 35
	v_readlane_b32 s29, v241, 36
	s_add_u32 s34, s28, s0
	s_addc_u32 s35, s29, 0
	s_cmp_eq_u32 s24, 0
	s_cselect_b64 s[38:39], -1, 0
	s_and_b64 s[0:1], s[38:39], exec
	s_mov_b32 s0, 0x1e800000
	s_cselect_b32 s0, 0x26800000, s0
	s_add_u32 s0, s74, s0
	s_addc_u32 s1, s75, 0
	s_lshl_b32 s27, s27, 10
	s_add_u32 s0, s0, s27
	v_ashrrev_i32_e32 v4, 2, v66
	s_addc_u32 s1, s1, 0
	s_lshl_b32 s27, s26, 7
	s_lshl_b32 s96, s26, 8
	v_bfi_b32 v68, -16, v4, v66
	s_waitcnt vmcnt(12)
	v_bfe_u32 v7, v66, 4, 2
	s_add_u32 s0, s0, s96
	v_readlane_b32 s28, v238, 35
	v_mul_lo_u32 v6, v68, s84
	v_and_b32_e32 v5, 63, v66
	s_addc_u32 s1, s1, 0
	s_or_b32 s44, s26, s28
	v_add_u32_e32 v6, 0, v6
	v_lshlrev_b32_e32 v50, 3, v7
	s_movk_i32 s28, 0xff74
	v_mov_b32_e32 v51, v1
	v_mad_u64_u32 v[52:53], s[28:29], v68, s28, v[6:7]
	s_waitcnt vmcnt(11)
	v_lshlrev_b32_e32 v13, 2, v5
	v_lshl_add_u64 v[54:55], s[0:1], 0, v[50:51]
	s_lshl_b32 s0, s24, 2
	v_readlane_b32 s56, v239, 32
	v_and_b32_e32 v11, 48, v66
	v_xor_b32_e32 v53, 64, v13
	s_movk_i32 s45, 0x8c
	s_or_b32 s0, s44, s0
	v_readlane_b32 s57, v239, 33
	v_add_u32_e32 v69, v6, v11
	v_lshlrev_b32_e32 v12, 2, v7
	v_mad_u64_u32 v[6:7], s[28:29], v68, s45, v[52:53]
	s_ashr_i32 s1, s0, 31
	v_readlane_b32 s58, v239, 34
	v_readlane_b32 s59, v239, 35
	v_readlane_b32 s60, v239, 36
	v_readlane_b32 s61, v239, 37
	s_mov_b64 s[48:49], s[56:57]
	v_readlane_b32 s28, v238, 7
	s_add_i32 s54, 0, 0x10000
	s_lshl_b64 s[0:1], s[0:1], 2
	s_mov_b64 s[50:51], s[58:59]
	v_lshl_add_u32 v74, v68, 2, s28
	v_add_u32_e32 v77, s28, v13
	s_add_u32 s28, s50, s0
	s_mov_b64 s[52:53], s[60:61]
	s_addc_u32 s29, s51, s1
	s_add_u32 s0, s52, s0
	s_addc_u32 s1, s53, s1
	global_load_dword v78, v1, s[28:29]
	global_load_dword v79, v1, s[0:1]
	v_and_b32_e32 v9, -16, v4
	v_and_b32_e32 v10, 56, v0
	v_lshl_add_u32 v72, v11, 1, v6
	v_add_u32_e32 v75, v6, v50
	v_lshlrev_b32_e32 v6, 1, v9
	v_lshlrev_b32_e32 v9, 2, v66
	v_lshlrev_b32_e32 v0, 1, v10
	v_add_u32_e32 v80, -4, v9
	v_add_u32_e32 v81, -8, v9
	v_add_u32_e32 v82, -16, v9
	v_subrev_u32_e32 v83, 32, v9
	v_subrev_u32_e32 v84, 64, v9
	v_add_u32_e32 v85, 0xffffff80, v9
	v_mul_u32_u24_e32 v9, 0x90, v10
	v_add_u32_e32 v10, 0x100, v66
	v_ashrrev_i32_e32 v87, 3, v10
	v_ashrrev_i32_e32 v90, 4, v10
	v_add_u32_e32 v10, 0x200, v66
	v_ashrrev_i32_e32 v92, 4, v10
	v_add_u32_e32 v10, 0x300, v66
	v_add_u32_e32 v3, 0, v3
	v_ashrrev_i32_e32 v88, 4, v66
	v_ashrrev_i32_e32 v94, 4, v10
	v_and_b32_e32 v88, 63, v66
	v_mov_b32_e32 v90, v88
	v_mov_b32_e32 v92, v88
	v_mov_b32_e32 v94, v88
	v_lshrrev_b32_e32 v89, 6, v66
	v_mul_u32_u24_e32 v89, 0x480, v89
	v_lshl_add_u32 v89, v88, 1, v89
	v_add_u32_e32 v91, 0x1200, v89
	v_add_u32_e32 v93, 0x2400, v89
	v_add_u32_e32 v95, 0x3600, v89
	v_or_b32_e32 v3, 2, v12
	v_cmp_le_i32_e64 s[58:59], v3, v68
	v_or_b32_e32 v3, 3, v12
	v_add_u32_e32 v4, 0, v0
	v_readlane_b32 s62, v239, 38
	v_readlane_b32 s63, v239, 39
	v_ashrrev_i32_e32 v86, 3, v66
	v_cmp_le_i32_e64 s[60:61], v3, v68
	v_or_b32_e32 v3, 16, v12
	v_cmp_eq_u32_e64 s[42:43], 0, v5
	v_mul_lo_u32 v7, v66, s45
	v_readlane_b32 s64, v239, 40
	v_readlane_b32 s65, v239, 41
	v_cmp_gt_u32_e64 s[44:45], 2, v5
	v_cmp_gt_u32_e64 s[46:47], 4, v5
	v_cmp_gt_u32_e64 s[48:49], 8, v5
	v_cmp_gt_u32_e64 s[50:51], 16, v5
	v_cmp_gt_u32_e64 s[52:53], 32, v5
	v_mad_u64_u32 v[56:57], s[0:1], v86, s84, v[4:5]
	v_lshl_add_u32 v5, v86, 1, 0
	v_cmp_le_i32_e64 s[62:63], v3, v68
	v_or_b32_e32 v3, 17, v12
	v_readlane_b32 s66, v239, 42
	v_readlane_b32 s67, v239, 43
	v_mad_u64_u32 v[58:59], s[0:1], v87, s84, v[4:5]
	v_cmp_le_i32_e64 s[64:65], v3, v68
	v_or_b32_e32 v3, 18, v12
	v_readlane_b32 s68, v239, 44
	v_readlane_b32 s69, v239, 45
	v_cmp_le_i32_e64 s[66:67], v3, v68
	v_or_b32_e32 v3, 19, v12
	s_lshl_b32 s0, s24, 3
	v_readlane_b32 s70, v239, 46
	v_readlane_b32 s71, v239, 47
	v_cmp_le_i32_e64 s[68:69], v3, v68
	v_or_b32_e32 v3, 32, v12
	s_add_u32 s0, s34, s0
	v_cmp_le_i32_e64 s[70:71], v3, v68
	v_or_b32_e32 v3, 33, v12
	s_addc_u32 s1, s35, 0
	s_lshl_b32 s26, s26, 1
	v_cmp_le_i32_e64 s[72:73], v3, v68
	v_or_b32_e32 v3, 34, v12
	s_add_u32 s0, s0, s26
	v_cmp_le_i32_e64 s[74:75], v3, v68
	v_or_b32_e32 v3, 35, v12
	s_addc_u32 s1, s1, 0
	v_cmp_le_i32_e64 s[76:77], v3, v68
	v_or_b32_e32 v3, 48, v12
	s_add_u32 s28, s34, s27
	v_cmp_le_i32_e64 s[78:79], v3, v68
	v_or_b32_e32 v3, 49, v12
	s_addc_u32 s29, s35, 0
	v_and_b32_e32 v8, 15, v66
	v_cmp_le_i32_e64 s[80:81], v3, v68
	v_or_b32_e32 v3, 50, v12
	v_lshl_add_u64 v[60:61], s[28:29], 0, v[0:1]
	s_add_u32 s28, s34, s96
	v_add3_u32 v6, 0, v6, v50
	v_lshl_add_u32 v4, v87, 1, 0
	v_mul_u32_u24_e32 v96, 0x90, v8
	v_cmp_le_i32_e64 s[82:83], v3, v68
	v_or_b32_e32 v3, 51, v12
	s_addc_u32 s29, s35, 0
	v_lshlrev_b32_e32 v0, 1, v2
	v_mov_b32_e32 v101, 0
	s_mov_b32 s21, 0
	v_cmp_gt_u32_e64 s[40:41], 64, v66
	v_add_u32_e32 v70, 0, v11
	v_xor_b32_e32 v71, 0x80, v13
	v_lshl_add_u32 v73, v11, 2, 0
	v_add_u32_e32 v51, 0, v13
	v_add_u32_e32 v76, s54, v13
	v_lshl_add_u32 v57, v86, 2, s54
	v_lshl_add_u32 v59, v87, 2, s54
	v_cmp_le_i32_e64 s[54:55], v12, v68
	v_cmp_lt_i32_e64 s[56:57], v12, v68
	v_cmp_le_i32_e64 s[84:85], v3, v68
	v_lshrrev_b32_e32 v132, 6, v66
	v_lshlrev_b32_e32 v132, 4, v132
	v_mov_b32_e32 v133, 0
	v_lshl_add_u64 v[62:63], s[28:29], 0, v[132:133]
	s_movk_i32 s96, 0x7c0
	v_add_u32_e32 v97, v5, v9
	v_add_u32_e32 v98, v4, v9
	v_add_u32_e32 v99, v6, v96
	v_add_u32_e32 v100, v67, v7
	v_mov_b32_e32 v2, 0
	v_mov_b32_e32 v3, v101
	v_mov_b32_e32 v4, v101
	v_mov_b32_e32 v5, v101
	v_mov_b32_e32 v6, 0
	v_mov_b32_e32 v7, v101
	v_mov_b32_e32 v8, v101
	v_mov_b32_e32 v9, v101
	v_mov_b32_e32 v10, 0
	v_mov_b32_e32 v11, v101
	v_mov_b32_e32 v12, v101
	v_mov_b32_e32 v13, v101
	s_waitcnt vmcnt(12)
	v_mov_b32_e32 v14, 0
	v_mov_b32_e32 v15, v101
	v_mov_b32_e32 v16, v101
	v_mov_b32_e32 v17, v101
	s_waitcnt vmcnt(11)
	v_mov_b32_e32 v18, 0
	v_mov_b32_e32 v19, v101
	v_mov_b32_e32 v20, v101
	v_mov_b32_e32 v21, v101
	s_waitcnt vmcnt(10)
	v_mov_b32_e32 v22, 0
	v_mov_b32_e32 v23, v101
	v_mov_b32_e32 v24, v101
	v_mov_b32_e32 v25, v101
	s_waitcnt vmcnt(9)
	v_mov_b32_e32 v26, 0
	v_mov_b32_e32 v27, v101
	v_mov_b32_e32 v28, v101
	v_mov_b32_e32 v29, v101
	s_waitcnt vmcnt(8)
	v_mov_b32_e32 v30, 0
	v_mov_b32_e32 v31, v101
	v_mov_b32_e32 v32, v101
	v_mov_b32_e32 v33, v101
	s_waitcnt lgkmcnt(0)
	s_barrier
	s_branch .LBB0_472

; __device__ __forceinline__ unsigned pack2(float a, float b) { const f32x2n v = {a, b}; const bf16x2n h = __builtin_convertvector(v, bf16x2n); return __builtin_bit_cast(unsigned, h); }
; __device__ void mx_mlstm(const Params& P, int l, int item, char* lds) {
;     ...
;             for (int it = 0; it < 2; ++it) {
;                 const int vi = tid + 256 * it, ii = vi >> 3, e = vi & 7, t = TROW(ii);
;                 float f[8];
;                 unpack8(*(const u32x4*)(pr + (size_t)t * PREST_LD + h * 64 + e * 8), f);
;                 *(u32x4*)(Q + ii * 72 + e * 8) = (u32x4){pack2(f[0] * 0.125f, f[1] * 0.125f), pack2(f[2] * 0.125f, f[3] * 0.125f), pack2(f[4] * 0.125f, f[5] * 0.125f), pack2(f[6] * 0.125f, f[7] * 0.125f)};
;                 const u32x4 kv = *(const u32x4*)(pr + (size_t)t * PREST_LD + 256 + h * 64 + e * 8);
;                 *(u32x4*)(KP + ii * 72 + e * 8) = kv;
;                 unpack8(kv, f);
;                 const float wi = WI[ii];
; #pragma unroll
;                 for (int x = 0; x < 8; ++x) KWT[(e * 8 + x) * 72 + ii] = f2bf(f[x] * wi);
;             }
; #pragma unroll
;             for (int it = 0; it < 4; ++it) {
;                 const int vi = tid + 256 * it, ii = vi >> 4, e = vi & 15, t = TROW(ii);
;                 const u32x4 vv = *(const u32x4*)(pr + (size_t)t * PREST_LD + 512 + h * 128 + e * 8);
;                 VT[(e * 8 + 0) * 72 + ii] = (bf16_t)(vv.x & 0xffff); VT[(e * 8 + 1) * 72 + ii] = (bf16_t)(vv.x >> 16);
;                 VT[(e * 8 + 2) * 72 + ii] = (bf16_t)(vv.y & 0xffff); VT[(e * 8 + 3) * 72 + ii] = (bf16_t)(vv.y >> 16);
;                 VT[(e * 8 + 4) * 72 + ii] = (bf16_t)(vv.z & 0xffff); VT[(e * 8 + 5) * 72 + ii] = (bf16_t)(vv.z >> 16);
;                 VT[(e * 8 + 6) * 72 + ii] = (bf16_t)(vv.w & 0xffff); VT[(e * 8 + 7) * 72 + ii] = (bf16_t)(vv.w >> 16);
;             }
.LBB0_476:
	s_or_b64 exec, exec, s[28:29]
	s_or_b32 s28, s97, 63
	v_sub_u32_e32 v0, s28, v86
	s_waitcnt vmcnt(7)
	v_add_u32_e32 v34, s21, v86
	v_cndmask_b32_e64 v0, v0, v34, s[38:39]
	s_waitcnt vmcnt(6)
	v_mad_i64_i32 v[38:39], s[26:27], v0, s3, v[60:61]
	global_load_dwordx4 v[34:37], v[38:39], off
	global_load_dwordx4 v[144:147], v[38:39], off offset:512
	v_sub_u32_e32 v132, s28, v87
	v_add_u32_e32 v133, s21, v87
	v_cndmask_b32_e64 v132, v132, v133, s[38:39]
	v_mad_i64_i32 v[134:135], s[26:27], v132, s3, v[60:61]
	global_load_dwordx4 v[148:151], v[134:135], off
	global_load_dwordx4 v[152:155], v[134:135], off offset:512
	v_sub_u32_e32 v132, s28, v88
	v_add_u32_e32 v133, s21, v88
	v_cndmask_b32_e64 v132, v132, v133, s[38:39]
	v_mad_i64_i32 v[136:137], s[26:27], v132, s3, v[62:63]
	global_load_dwordx4 v[156:159], v[136:137], off offset:1024
	v_sub_u32_e32 v132, s28, v90
	v_add_u32_e32 v133, s21, v90
	v_cndmask_b32_e64 v132, v132, v133, s[38:39]
	v_mad_i64_i32 v[138:139], s[26:27], v132, s3, v[62:63]
	global_load_dwordx4 v[160:163], v[138:139], off offset:1088
	v_sub_u32_e32 v132, s28, v92
	v_add_u32_e32 v133, s21, v92
	v_cndmask_b32_e64 v132, v132, v133, s[38:39]
	v_mad_i64_i32 v[140:141], s[26:27], v132, s3, v[62:63]
	global_load_dwordx4 v[164:167], v[140:141], off offset:1152
	v_sub_u32_e32 v132, s28, v94
	v_add_u32_e32 v133, s21, v94
	v_cndmask_b32_e64 v132, v132, v133, s[38:39]
	v_mad_i64_i32 v[142:143], s[26:27], v132, s3, v[62:63]
	global_load_dwordx4 v[168:171], v[142:143], off offset:1216
	s_waitcnt lgkmcnt(0)
	s_barrier
; __device__ __forceinline__ unsigned pack2(float a, float b) { const f32x2n v = {a, b}; const bf16x2n h = __builtin_convertvector(v, bf16x2n); return __builtin_bit_cast(unsigned, h); }
; __device__ void mx_mlstm(const Params& P, int l, int item, char* lds) {
;     ...
;             for (int it = 0; it < 2; ++it) {
;                 const int vi = tid + 256 * it, ii = vi >> 3, e = vi & 7, t = TROW(ii);
;                 float f[8];
;                 unpack8(*(const u32x4*)(pr + (size_t)t * PREST_LD + h * 64 + e * 8), f);
;                 *(u32x4*)(Q + ii * 72 + e * 8) = (u32x4){pack2(f[0] * 0.125f, f[1] * 0.125f), pack2(f[2] * 0.125f, f[3] * 0.125f), pack2(f[4] * 0.125f, f[5] * 0.125f), pack2(f[6] * 0.125f, f[7] * 0.125f)};
;                 const u32x4 kv = *(const u32x4*)(pr + (size_t)t * PREST_LD + 256 + h * 64 + e * 8);
;                 *(u32x4*)(KP + ii * 72 + e * 8) = kv;
;                 unpack8(kv, f);
;                 const float wi = WI[ii];
; #pragma unroll
;                 for (int x = 0; x < 8; ++x) KWT[(e * 8 + x) * 72 + ii] = f2bf(f[x] * wi);
;             }
; #pragma unroll
;             for (int it = 0; it < 4; ++it) {
;                 const int vi = tid + 256 * it, ii = vi >> 4, e = vi & 15, t = TROW(ii);
;                 const u32x4 vv = *(const u32x4*)(pr + (size_t)t * PREST_LD + 512 + h * 128 + e * 8);
;                 VT[(e * 8 + 0) * 72 + ii] = (bf16_t)(vv.x & 0xffff); VT[(e * 8 + 1) * 72 + ii] = (bf16_t)(vv.x >> 16);
;                 VT[(e * 8 + 2) * 72 + ii] = (bf16_t)(vv.y & 0xffff); VT[(e * 8 + 3) * 72 + ii] = (bf16_t)(vv.y >> 16);
;                 VT[(e * 8 + 4) * 72 + ii] = (bf16_t)(vv.z & 0xffff); VT[(e * 8 + 5) * 72 + ii] = (bf16_t)(vv.z >> 16);
;                 VT[(e * 8 + 6) * 72 + ii] = (bf16_t)(vv.w & 0xffff); VT[(e * 8 + 7) * 72 + ii] = (bf16_t)(vv.w >> 16);
;             }
;             __syncthreads();
;             f32x4 sacc[4];
; #pragma unroll
;             for (int st = 0; st < 4; ++st) sacc[st] = (f32x4){0.f, 0.f, 0.f, 0.f};
; #pragma unroll
;             for (int ks = 0; ks < 2; ++ks) {
;                 const bf16x8 qf = ldfrag(Q + i * 72 + ks * 32 + fq * 8);
; #pragma unroll
;                 for (int st = 0; st < 4; ++st) sacc[st] = mfma16(ldfrag(KP + (st * 16 + fr) * 72 + ks * 32 + fq * 8), qf, sacc[st]);
;             }
	v_add_u32_e32 v102, v70, v96
	v_mov_b32_e32 v103, 0
	s_waitcnt vmcnt(7)
	v_lshlrev_b32_e32 v40, 16, v34
	v_and_b32_e32 v41, 0xffff0000, v34
	v_pk_mul_f32 v[40:41], v[40:41], s[2:3] op_sel_hi:[1,0]
	s_nop 0
	v_cvt_pk_bf16_f32 v34, v40, v41
	v_lshlrev_b32_e32 v40, 16, v35
	v_and_b32_e32 v41, 0xffff0000, v35
	v_pk_mul_f32 v[40:41], v[40:41], s[2:3] op_sel_hi:[1,0]
	s_nop 0
	v_cvt_pk_bf16_f32 v35, v40, v41
	v_lshlrev_b32_e32 v40, 16, v36
	v_and_b32_e32 v41, 0xffff0000, v36
	v_pk_mul_f32 v[40:41], v[40:41], s[2:3] op_sel_hi:[1,0]
	s_nop 0
	v_cvt_pk_bf16_f32 v36, v40, v41
	v_lshlrev_b32_e32 v40, 16, v37
	v_and_b32_e32 v41, 0xffff0000, v37
	v_pk_mul_f32 v[40:41], v[40:41], s[2:3] op_sel_hi:[1,0]
	s_nop 0
	v_cvt_pk_bf16_f32 v37, v40, v41
	ds_write_b128 v56, v[34:37]
	s_waitcnt vmcnt(6)
	ds_write_b128 v56, v[144:147] offset:9216
	ds_read_b32 v41, v57
	v_lshlrev_b32_e32 v0, 16, v144
	v_and_b32_e32 v144, 0xffff0000, v144
	v_lshlrev_b32_e32 v38, 16, v145
	v_and_b32_e32 v145, 0xffff0000, v145
	s_waitcnt lgkmcnt(0)
	v_mul_f32_e32 v0, v41, v0
	v_cvt_pk_bf16_f32 v0, v0, s0
	ds_write_b16 v97, v0 offset:18432
	v_mul_f32_e32 v0, v41, v144
	v_cvt_pk_bf16_f32 v0, v0, s0
	ds_write_b16 v97, v0 offset:18576
	v_mul_f32_e32 v0, v41, v38
	v_cvt_pk_bf16_f32 v0, v0, s0
	ds_write_b16 v97, v0 offset:18720
	v_mul_f32_e32 v0, v41, v145
	v_lshlrev_b32_e32 v39, 16, v146
	v_cvt_pk_bf16_f32 v0, v0, s0
	ds_write_b16 v97, v0 offset:18864
	v_mul_f32_e32 v0, v41, v39
	v_and_b32_e32 v146, 0xffff0000, v146
	v_cvt_pk_bf16_f32 v0, v0, s0
	ds_write_b16 v97, v0 offset:19008
	v_mul_f32_e32 v0, v41, v146
	v_lshlrev_b32_e32 v40, 16, v147
	v_cvt_pk_bf16_f32 v0, v0, s0
	ds_write_b16 v97, v0 offset:19152
	v_mul_f32_e32 v0, v41, v40
	v_and_b32_e32 v147, 0xffff0000, v147
	v_cvt_pk_bf16_f32 v0, v0, s0
	ds_write_b16 v97, v0 offset:19296
	v_mul_f32_e32 v0, v41, v147
	v_cvt_pk_bf16_f32 v0, v0, s0
	ds_write_b16 v97, v0 offset:19440
	s_waitcnt vmcnt(5)
	v_lshlrev_b32_e32 v40, 16, v148
	v_and_b32_e32 v41, 0xffff0000, v148
	v_pk_mul_f32 v[40:41], v[40:41], s[2:3] op_sel_hi:[1,0]
	s_nop 0
	v_cvt_pk_bf16_f32 v148, v40, v41
	v_lshlrev_b32_e32 v40, 16, v149
	v_and_b32_e32 v41, 0xffff0000, v149
	v_pk_mul_f32 v[40:41], v[40:41], s[2:3] op_sel_hi:[1,0]
	s_nop 0
	v_cvt_pk_bf16_f32 v149, v40, v41
	v_lshlrev_b32_e32 v40, 16, v150
	v_and_b32_e32 v41, 0xffff0000, v150
	v_pk_mul_f32 v[40:41], v[40:41], s[2:3] op_sel_hi:[1,0]
	s_nop 0
	v_cvt_pk_bf16_f32 v150, v40, v41
	v_lshlrev_b32_e32 v40, 16, v151
	v_and_b32_e32 v41, 0xffff0000, v151
	v_pk_mul_f32 v[40:41], v[40:41], s[2:3] op_sel_hi:[1,0]
	s_nop 0
	v_cvt_pk_bf16_f32 v151, v40, v41
	ds_write_b128 v58, v[148:151]
	s_waitcnt vmcnt(4)
	ds_write_b128 v58, v[152:155] offset:9216
	ds_read_b32 v41, v59
	v_lshlrev_b32_e32 v0, 16, v152
	v_and_b32_e32 v152, 0xffff0000, v152
	v_lshlrev_b32_e32 v38, 16, v153
	v_and_b32_e32 v153, 0xffff0000, v153
	s_waitcnt lgkmcnt(0)
	v_mul_f32_e32 v0, v41, v0
	v_cvt_pk_bf16_f32 v0, v0, s0
	ds_write_b16 v98, v0 offset:18432
	v_mul_f32_e32 v0, v41, v152
	v_cvt_pk_bf16_f32 v0, v0, s0
	ds_write_b16 v98, v0 offset:18576
	v_mul_f32_e32 v0, v41, v38
	v_cvt_pk_bf16_f32 v0, v0, s0
	ds_write_b16 v98, v0 offset:18720
	v_mul_f32_e32 v0, v41, v153
	v_lshlrev_b32_e32 v39, 16, v154
	v_cvt_pk_bf16_f32 v0, v0, s0
	ds_write_b16 v98, v0 offset:18864
	v_mul_f32_e32 v0, v41, v39
	v_and_b32_e32 v154, 0xffff0000, v154
	v_cvt_pk_bf16_f32 v0, v0, s0
	ds_write_b16 v98, v0 offset:19008
	v_mul_f32_e32 v0, v41, v154
	v_lshlrev_b32_e32 v40, 16, v155
	v_cvt_pk_bf16_f32 v0, v0, s0
	ds_write_b16 v98, v0 offset:19152
	v_mul_f32_e32 v0, v41, v40
	v_and_b32_e32 v155, 0xffff0000, v155
	v_cvt_pk_bf16_f32 v0, v0, s0
	ds_write_b16 v98, v0 offset:19296
	v_mul_f32_e32 v0, v41, v155
	v_cvt_pk_bf16_f32 v0, v0, s0
	ds_write_b16 v98, v0 offset:19440
	s_waitcnt vmcnt(3)
	ds_write_b16 v89, v156 offset:27648
	ds_write_b16_d16_hi v89, v156 offset:27792
	ds_write_b16 v89, v157 offset:27936
	ds_write_b16_d16_hi v89, v157 offset:28080
	ds_write_b16 v89, v158 offset:28224
	ds_write_b16_d16_hi v89, v158 offset:28368
	ds_write_b16 v89, v159 offset:28512
	ds_write_b16_d16_hi v89, v159 offset:28656
	s_waitcnt vmcnt(2)
	ds_write_b16 v91, v160 offset:27648
	ds_write_b16_d16_hi v91, v160 offset:27792
	ds_write_b16 v91, v161 offset:27936
	ds_write_b16_d16_hi v91, v161 offset:28080
	ds_write_b16 v91, v162 offset:28224
	ds_write_b16_d16_hi v91, v162 offset:28368
	ds_write_b16 v91, v163 offset:28512
	ds_write_b16_d16_hi v91, v163 offset:28656
	s_waitcnt vmcnt(1)
	ds_write_b16 v93, v164 offset:27648
	ds_write_b16_d16_hi v93, v164 offset:27792
	ds_write_b16 v93, v165 offset:27936
	ds_write_b16_d16_hi v93, v165 offset:28080
	ds_write_b16 v93, v166 offset:28224
	ds_write_b16_d16_hi v93, v166 offset:28368
	ds_write_b16 v93, v167 offset:28512
	ds_write_b16_d16_hi v93, v167 offset:28656
	v_mov_b32_e32 v0, 0
	s_waitcnt vmcnt(0)
	ds_write_b16 v95, v168 offset:27648
	ds_write_b16_d16_hi v95, v168 offset:27792
	ds_write_b16 v95, v169 offset:27936
	ds_write_b16_d16_hi v95, v169 offset:28080
	ds_write_b16 v95, v170 offset:28224
	ds_write_b16_d16_hi v95, v170 offset:28368
	ds_write_b16 v95, v171 offset:28512
	ds_write_b16_d16_hi v95, v171 offset:28656
	s_waitcnt lgkmcnt(0)
	s_barrier
	ds_read_b128 v[42:45], v102 offset:11520
	ds_read_b128 v[46:49], v102 offset:13824
	ds_read_b128 v[34:37], v69
	ds_read_b128 v[38:41], v102 offset:9216
	s_waitcnt lgkmcnt(1)
	v_mfma_f32_16x16x32_bf16 v[104:107], v[46:49], v[34:37], 0
	ds_read_b128 v[46:49], v102 offset:16128
	s_waitcnt lgkmcnt(1)
	v_mfma_f32_16x16x32_bf16 v[38:41], v[38:41], v[34:37], 0
	v_mfma_f32_16x16x32_bf16 v[42:45], v[42:45], v[34:37], 0
	s_waitcnt lgkmcnt(0)
	v_mfma_f32_16x16x32_bf16 v[34:37], v[46:49], v[34:37], 0
	ds_read_b128 v[108:111], v69 offset:64
	ds_read_b128 v[46:49], v102 offset:9280
	ds_read2st64_b32 v[64:65], v52 offset0:254 offset1:255
	s_waitcnt lgkmcnt(1)
	v_mfma_f32_16x16x32_bf16 v[46:49], v[46:49], v[108:111], v[38:41]
	s_nop 2
	ds_read_b128 v[38:41], v102 offset:11584
	s_waitcnt lgkmcnt(0)
	v_mfma_f32_16x16x32_bf16 v[42:45], v[38:41], v[108:111], v[42:45]
	ds_read_b128 v[38:41], v102 offset:13888
	s_waitcnt lgkmcnt(0)
	v_mfma_f32_16x16x32_bf16 v[38:41], v[38:41], v[108:111], v[104:107]
	s_nop 2
	ds_read_b128 v[104:107], v102 offset:16192
	s_waitcnt lgkmcnt(0)
	v_mfma_f32_16x16x32_bf16 v[34:37], v[104:107], v[108:111], v[34:37]
	s_and_saveexec_b64 s[28:29], s[54:55]
	s_cbranch_execz .LBB0_506
	ds_read_b32 v103, v70 offset:64768
	s_waitcnt lgkmcnt(0)
	v_sub_f32_e32 v103, v103, v64
	v_mul_f32_e32 v103, 0x3fb8aa3b, v103
	v_exp_f32_e32 v103, v103
	s_nop 0
	v_mul_f32_e32 v103, v46, v103
	s_or_b64 exec, exec, s[28:29]
	v_mov_b32_e32 v46, 0
	s_and_saveexec_b64 s[28:29], s[56:57]
	s_cbranch_execnz .LBB0_507
